# c20 + natt softmax max/sum lane^16, lane^32 butterflies through v_permlane16/32_swap (7 of 8 sites)
# speedup vs baseline: 1.0056x; 1.0005x over previous
; #define LAS __attribute__((address_space(3)))
; __device__ __forceinline__ float shfl_lane(float v, int srclane) { return __int_as_float(__builtin_amdgcn_ds_bpermute(srclane << 2, __float_as_int(v))); }
; __device__ __forceinline__ void p_natt(const Frame& F0, const bf16* Q, const bf16* Kb, const bf16* V, const float* rpb, bf16* O, int L) {
;     ...
;             if (kr >= rs && kr <= rs + 7) {
;                 const int dy = kr - r + 7;
;                 int Lq = Ln; asm volatile("" : "+v"(Lq));
;                 const int g = Lq >> 4, l15 = Lq & 15, q4 = l15 >> 2, p4 = Lq & 3;
; #pragma unroll
;                 for (int jt = 0; jt < 2; ++jt) {
;                     const int j = 2 * chf + jt, kstart = (j == 0) ? 0 : (j == 1 ? 8 : (j == 2 ? 24 : 32)), qcol = 16 * j + l15;
;                     int wst = qcol - 8; wst = wst < 0 ? 0 : (wst > 48 ? 48 : wst);
;                     f32x4 sA = {0.f, 0.f, 0.f, 0.f}, sB = {0.f, 0.f, 0.f, 0.f};
;                     const LAS unsigned char* ka = kb + (kstart + 8 * q4 + p4) * PB + 16 * g;
; #pragma unroll
;                     for (int kd = 0; kd < 4; ++kd) { const bf16x8 fa = *(const LAS bf16x8*)(ka + 64 * kd), fb = *(const LAS bf16x8*)(ka + 4 * PB + 64 * kd);
;                         sA = __builtin_amdgcn_mfma_f32_16x16x32_bf16(fa, qf[jt][kd], sA, 0, 0, 0); sB = __builtin_amdgcn_mfma_f32_16x16x32_bf16(fb, qf[jt][kd], sB, 0, 0, 0); }
;                     float sv[8]; float mx = mrun[jt];
;                     const LAS float* rpq = rp + dy * 31 + (kstart + 8 * g - qcol + 15); const unsigned wrel = (unsigned)(kstart + 8 * g - wst);
; #pragma unroll
;                     for (int e = 0; e < 8; ++e) { const bool ok = (wrel + (unsigned)e) < 16u;
;                         const float x = (e < 4 ? sA[e] : sB[e - 4]) + rpq[e]; sv[e] = ok ? x : -3.0e38f; mx = fmaxf(mx, sv[e]); }
;                     mx = fmaxf(mx, shfl_lane(mx, Lq ^ 16)); mx = fmaxf(mx, shfl_lane(mx, Lq ^ 32));
;                     float alpha = 1.0f;
;                     if (__builtin_amdgcn_ballot_w64(mx > mrun[jt] + 8.0f) != 0ull) { alpha = __expf(mrun[jt] - mx); mrun[jt] = mx;
; #pragma unroll
;                         for (int dt = 0; dt < 8; ++dt) oacc[jt][dt] = oacc[jt][dt] * alpha; }
.LBB0_651:
	s_add_i32 s34, s16, s31
	s_cmp_lt_i32 s34, s21
	s_cselect_b64 s[0:1], -1, 0
	s_cmp_gt_i32 s34, s27
	s_cselect_b64 s[18:19], -1, 0
	s_or_b64 s[0:1], s[0:1], s[18:19]
	s_and_b64 vcc, exec, s[0:1]
	s_cbranch_vccnz .LBB0_654
	v_mov_b32_e32 v130, v1
	s_mul_hi_u32 s0, s31, 0xaaaaaaab
	s_lshr_b32 s0, s0, 1
	v_bfe_u32 v137, v130, 2, 2
	v_and_b32_e32 v141, 3, v130
	v_ashrrev_i32_e32 v132, 1, v130
	v_lshl_or_b32 v144, v137, 3, v141
	v_and_b32_e32 v138, -8, v132
	v_lshlrev_b32_e32 v132, 2, v130
	s_mul_i32 s0, s0, 0xfffe6800
	v_xor_b32_e32 v140, 64, v132
	v_xor_b32_e32 v139, 0x80, v132
	v_add_u32_e32 v132, s24, v144
	s_add_i32 s1, s20, 0
	v_and_b32_e32 v143, -16, v130
	v_mul_u32_u24_e32 v132, 0x110, v132
	s_add_i32 s1, s1, s0
	v_add3_u32 v145, v132, v143, s1
	ds_read_b128 v[132:135], v145
	ds_read_b128 v[180:183], v145 offset:1088
	ds_read_b128 v[184:187], v145 offset:64
	ds_read_b128 v[188:191], v145 offset:1152
	s_waitcnt lgkmcnt(3)
	v_mfma_f32_16x16x32_bf16 v[132:135], v[132:135], v[26:29], 0
	v_and_or_b32 v142, v130, 15, s22
	s_add_i32 s19, s29, 0
	v_max_i32_e32 v130, 8, v142
	s_waitcnt lgkmcnt(2)
	v_mfma_f32_16x16x32_bf16 v[180:183], v[180:183], v[26:29], 0
	s_waitcnt lgkmcnt(1)
	v_mfma_f32_16x16x32_bf16 v[132:135], v[184:187], v[30:33], v[132:135]
	s_waitcnt lgkmcnt(0)
	v_mfma_f32_16x16x32_bf16 v[180:183], v[188:191], v[30:33], v[180:183]
	ds_read_b128 v[184:187], v145 offset:128
	ds_read_b128 v[188:191], v145 offset:1216
	s_waitcnt lgkmcnt(1)
	v_mfma_f32_16x16x32_bf16 v[132:135], v[184:187], v[34:37], v[132:135]
	s_waitcnt lgkmcnt(0)
	v_mfma_f32_16x16x32_bf16 v[180:183], v[188:191], v[34:37], v[180:183]
	ds_read_b128 v[184:187], v145 offset:192
	ds_read_b128 v[188:191], v145 offset:1280
	v_add_u32_e32 v145, s24, v138
	v_sub_u32_e32 v146, v145, v142
	s_waitcnt lgkmcnt(1)
	v_mfma_f32_16x16x32_bf16 v[184:187], v[184:187], v[38:41], v[132:135]
	v_sub_u32_e32 v130, v145, v130
	v_add_u32_e32 v145, 8, v130
	v_cmp_gt_u32_e32 vcc, 16, v145
	s_waitcnt lgkmcnt(0)
	v_mfma_f32_16x16x32_bf16 v[132:135], v[188:191], v[38:41], v[180:183]
	s_nop 2
	v_lshl_add_u32 v182, v146, 2, s19
	v_add_u32_e32 v146, 0x19ba0, v182
	ds_read2_b32 v[146:147], v146 offset1:1
	s_waitcnt lgkmcnt(0)
	v_add_f32_e32 v145, v184, v146
	v_cndmask_b32_e32 v146, v231, v145, vcc
	v_add_u32_e32 v145, 9, v130
	v_cmp_gt_u32_e32 vcc, 16, v145
	v_add_f32_e32 v145, v185, v147
	v_add_u32_e32 v147, 10, v130
	v_cndmask_b32_e32 v145, v231, v145, vcc
	v_cmp_gt_u32_e32 vcc, 16, v147
	v_add_u32_e32 v147, 0x19ba8, v182
	ds_read2_b32 v[170:171], v147 offset1:1
	v_max3_f32 v180, v136, v146, v145
	s_waitcnt lgkmcnt(0)
	v_add_f32_e32 v147, v186, v170
	v_cndmask_b32_e32 v170, v231, v147, vcc
	v_add_u32_e32 v147, 11, v130
	v_cmp_gt_u32_e32 vcc, 16, v147
	v_add_f32_e32 v147, v187, v171
	v_add_u32_e32 v171, 12, v130
	v_cndmask_b32_e32 v147, v231, v147, vcc
	v_cmp_gt_u32_e32 vcc, 16, v171
	v_add_u32_e32 v171, 0x19bb0, v182
	v_max3_f32 v183, v180, v170, v147
	ds_read2_b32 v[180:181], v171 offset1:1
	s_waitcnt lgkmcnt(0)
	v_add_f32_e32 v132, v132, v180
	v_cndmask_b32_e32 v171, v231, v132, vcc
	v_add_u32_e32 v132, 13, v130
	v_cmp_gt_u32_e32 vcc, 16, v132
	v_add_f32_e32 v132, v133, v181
	v_add_u32_e32 v133, 14, v130
	v_cndmask_b32_e32 v132, v231, v132, vcc
	v_cmp_gt_u32_e32 vcc, 16, v133
	v_add_u32_e32 v133, 0x19bb8, v182
	ds_read2_b32 v[180:181], v133 offset1:1
	v_add_u32_e32 v130, 15, v130
	v_max3_f32 v183, v183, v171, v132
	s_waitcnt lgkmcnt(0)
	v_add_f32_e32 v133, v134, v180
	v_cndmask_b32_e32 v133, v231, v133, vcc
	v_cmp_gt_u32_e32 vcc, 16, v130
	v_add_f32_e32 v130, v135, v181
	s_nop 0
	v_cndmask_b32_e32 v134, v231, v130, vcc
	v_max3_f32 v130, v183, v133, v134
	v_mov_b32_e32 v135, v130
	s_nop 1
	v_permlane16_swap_b32_e32 v130, v135
	s_nop 0
	s_waitcnt lgkmcnt(0)
	v_max_f32_e32 v135, v135, v135
	v_max_f32_e32 v130, v130, v135
	v_mov_b32_e32 v135, v130
	s_nop 1
	v_permlane32_swap_b32_e32 v130, v135
	s_nop 0
	s_waitcnt lgkmcnt(0)
	v_max_f32_e32 v135, v135, v135
	v_max_f32_e32 v180, v130, v135
	v_add_f32_e32 v130, 0x41000000, v136
	v_cmp_gt_f32_e32 vcc, v180, v130
	v_mov_b32_e32 v130, 1.0
	s_cbranch_vccz .LBB0_655
	v_sub_f32_e32 v135, v136, v180
	v_mul_f32_e32 v135, 0x3fb8aa3b, v135
	v_exp_f32_e32 v136, v135
	s_nop 0
	v_pk_mul_f32 v[128:129], v[128:129], v[136:137] op_sel_hi:[1,0]
	v_pk_mul_f32 v[126:127], v[126:127], v[136:137] op_sel_hi:[1,0]
	v_pk_mul_f32 v[124:125], v[124:125], v[136:137] op_sel_hi:[1,0]
	v_pk_mul_f32 v[122:123], v[122:123], v[136:137] op_sel_hi:[1,0]
	v_pk_mul_f32 v[120:121], v[120:121], v[136:137] op_sel_hi:[1,0]
	v_pk_mul_f32 v[118:119], v[118:119], v[136:137] op_sel_hi:[1,0]
	v_pk_mul_f32 v[112:113], v[112:113], v[136:137] op_sel_hi:[1,0]
	v_pk_mul_f32 v[110:111], v[110:111], v[136:137] op_sel_hi:[1,0]
	v_pk_mul_f32 v[104:105], v[104:105], v[136:137] op_sel_hi:[1,0]
	v_pk_mul_f32 v[102:103], v[102:103], v[136:137] op_sel_hi:[1,0]
	v_pk_mul_f32 v[92:93], v[92:93], v[136:137] op_sel_hi:[1,0]
	v_pk_mul_f32 v[90:91], v[90:91], v[136:137] op_sel_hi:[1,0]
	v_pk_mul_f32 v[88:89], v[88:89], v[136:137] op_sel_hi:[1,0]
	v_pk_mul_f32 v[86:87], v[86:87], v[136:137] op_sel_hi:[1,0]
	v_pk_mul_f32 v[84:85], v[84:85], v[136:137] op_sel_hi:[1,0]
	v_pk_mul_f32 v[82:83], v[82:83], v[136:137] op_sel_hi:[1,0]
	s_branch .LBB0_656

; __device__ __forceinline__ void p_natt(const Frame& F0, const bf16* Q, const bf16* Kb, const bf16* V, const float* rpb, bf16* O, int L) {
;     ...
;                 for (int jt = 0; jt < 2; ++jt) {
;                     const int j = 2 * chf + jt, kstart = (j == 0) ? 0 : (j == 1 ? 8 : (j == 2 ? 24 : 32)), qcol = 16 * j + l15;
;                     int wst = qcol - 8; wst = wst < 0 ? 0 : (wst > 48 ? 48 : wst);
;                     f32x4 sA = {0.f, 0.f, 0.f, 0.f}, sB = {0.f, 0.f, 0.f, 0.f};
;                     const LAS unsigned char* ka = kb + (kstart + 8 * q4 + p4) * PB + 16 * g;
; #pragma unroll
;                     for (int kd = 0; kd < 4; ++kd) { const bf16x8 fa = *(const LAS bf16x8*)(ka + 64 * kd), fb = *(const LAS bf16x8*)(ka + 4 * PB + 64 * kd);
;                         sA = __builtin_amdgcn_mfma_f32_16x16x32_bf16(fa, qf[jt][kd], sA, 0, 0, 0); sB = __builtin_amdgcn_mfma_f32_16x16x32_bf16(fb, qf[jt][kd], sB, 0, 0, 0); }
;                     float sv[8]; float mx = mrun[jt];
;                     const LAS float* rpq = rp + dy * 31 + (kstart + 8 * g - qcol + 15); const unsigned wrel = (unsigned)(kstart + 8 * g - wst);
; #pragma unroll
;                     for (int e = 0; e < 8; ++e) { const bool ok = (wrel + (unsigned)e) < 16u;
;                         const float x = (e < 4 ? sA[e] : sB[e - 4]) + rpq[e]; sv[e] = ok ? x : -3.0e38f; mx = fmaxf(mx, sv[e]); }
;                     mx = fmaxf(mx, shfl_lane(mx, Lq ^ 16)); mx = fmaxf(mx, shfl_lane(mx, Lq ^ 32));
;     ...
;                     mx = mrun[jt];
;                     float ps = 0.f;
; #pragma unroll
;                     for (int e = 0; e < 8; ++e) { sv[e] = __expf(sv[e] - mx); ps += sv[e]; }
;                     ps += shfl_lane(ps, Lq ^ 16); ps += shfl_lane(ps, Lq ^ 32);
;                     lrun[jt] = lrun[jt] * alpha + ps;
;                     u32x4 pw; pw.x = pk2(sv[0], sv[1]); pw.y = pk2(sv[2], sv[3]); pw.z = pk2(sv[4], sv[5]); pw.w = pk2(sv[6], sv[7]);
;                     const bf16x8 pf = __builtin_bit_cast(bf16x8, pw);
;                     const LAS unsigned char* va = vb + (kstart + 8 * g + q4) * PB + 8 * p4;
; #pragma unroll
;                     for (int dt = 0; dt < 8; ++dt) { const bf16x8 vf = cat8(tr_read(va + 32 * dt), tr_read(va + 4 * PB + 32 * dt));
;                         oacc[jt][dt] = __builtin_amdgcn_mfma_f32_16x16x32_bf16(vf, pf, oacc[jt][dt], 0, 0, 0); }
.LBB0_656:
	v_sub_f32_e32 v135, v146, v180
	v_mul_f32_e32 v135, 0x3fb8aa3b, v135
	v_sub_f32_e32 v145, v145, v180
	v_exp_f32_e32 v135, v135
	v_mul_f32_e32 v145, 0x3fb8aa3b, v145
	v_exp_f32_e32 v181, v145
	v_sub_f32_e32 v132, v132, v180
	v_add_f32_e32 v146, 0, v135
	v_sub_f32_e32 v133, v133, v180
	v_add_f32_e32 v145, v181, v146
	v_sub_f32_e32 v146, v170, v180
	v_mul_f32_e32 v146, 0x3fb8aa3b, v146
	v_exp_f32_e32 v170, v146
	v_sub_f32_e32 v146, v147, v180
	v_mul_f32_e32 v146, 0x3fb8aa3b, v146
	v_exp_f32_e32 v147, v146
	v_sub_f32_e32 v146, v171, v180
	v_mul_f32_e32 v146, 0x3fb8aa3b, v146
	v_exp_f32_e32 v171, v146
	v_mul_f32_e32 v132, 0x3fb8aa3b, v132
	v_mul_f32_e32 v133, 0x3fb8aa3b, v133
	v_exp_f32_e32 v182, v132
	v_exp_f32_e32 v183, v133
	v_sub_f32_e32 v133, v134, v180
	v_add_f32_e32 v145, v170, v145
	v_mul_f32_e32 v133, 0x3fb8aa3b, v133
	v_add_f32_e32 v145, v147, v145
	v_exp_f32_e32 v184, v133
	v_add_f32_e32 v145, v171, v145
	v_add_f32_e32 v132, v182, v145
	v_add_f32_e32 v132, v183, v132
	v_add_f32_e32 v132, v184, v132
	v_mov_b32_e32 v133, v132
	s_nop 1
	v_permlane16_swap_b32_e32 v132, v133
	s_nop 0
	s_add_i32 s18, s20, s0
	v_lshlrev_b32_e32 v141, 3, v141
	s_add_i32 s18, s18, 0
	v_cvt_pk_bf16_f32 v134, v171, v182
	s_waitcnt lgkmcnt(0)
	v_add_f32_e32 v145, v132, v133
	v_cvt_pk_bf16_f32 v133, v170, v147
	v_add3_u32 v147, s24, v137, v138
	v_mul_lo_u32 v147, v147, s38
	v_add3_u32 v147, v147, v141, s18
	v_cvt_pk_bf16_f32 v132, v135, v181
	v_cvt_pk_bf16_f32 v135, v183, v184
	ds_read_b64_tr_b16 v[184:185], v147 offset:18496
	ds_read_b64_tr_b16 v[182:183], v147 offset:17408
	ds_read_b64_tr_b16 v[186:187], v147 offset:17440
	s_waitcnt lgkmcnt(1)
	v_mfma_f32_16x16x32_bf16 v[126:129], v[182:185], v[132:135], v[126:129]
	ds_read_b64_tr_b16 v[188:189], v147 offset:18528
	ds_read_b64_tr_b16 v[182:183], v147 offset:17472
	ds_read_b64_tr_b16 v[184:185], v147 offset:18560
	ds_bpermute_b32 v146, v139, v145
	s_waitcnt lgkmcnt(1)
	v_mfma_f32_16x16x32_bf16 v[118:121], v[182:185], v[132:135], v[118:121]
	ds_read_b64_tr_b16 v[182:183], v147 offset:17504
	ds_read_b64_tr_b16 v[184:185], v147 offset:18592
	s_waitcnt lgkmcnt(0)
	v_mfma_f32_16x16x32_bf16 v[110:113], v[182:185], v[132:135], v[110:113]
	ds_read_b64_tr_b16 v[182:183], v147 offset:17536
	ds_read_b64_tr_b16 v[184:185], v147 offset:18624
	s_waitcnt lgkmcnt(0)
	v_mfma_f32_16x16x32_bf16 v[102:105], v[182:185], v[132:135], v[102:105]
	ds_read_b64_tr_b16 v[182:183], v147 offset:17568
	ds_read_b64_tr_b16 v[184:185], v147 offset:18656
	s_waitcnt lgkmcnt(0)
	v_mfma_f32_16x16x32_bf16 v[90:93], v[182:185], v[132:135], v[90:93]
	ds_read_b64_tr_b16 v[182:183], v147 offset:17600
	ds_read_b64_tr_b16 v[184:185], v147 offset:18688
	s_waitcnt lgkmcnt(0)
	v_mfma_f32_16x16x32_bf16 v[86:89], v[182:185], v[132:135], v[86:89]
	ds_read_b64_tr_b16 v[182:183], v147 offset:17632
	ds_read_b64_tr_b16 v[184:185], v147 offset:18720
	v_or_b32_e32 v147, 16, v142
	v_mfma_f32_16x16x32_bf16 v[122:125], v[186:189], v[132:135], v[122:125]
	s_waitcnt lgkmcnt(0)
	v_mfma_f32_16x16x32_bf16 v[82:85], v[182:185], v[132:135], v[82:85]
	v_add_u32_e32 v132, s25, v144
	v_mul_u32_u24_e32 v132, 0x110, v132
	v_add3_u32 v143, v132, v143, s18
	ds_read_b128 v[132:135], v143
	ds_read_b128 v[182:185], v143 offset:1088
	ds_read_b128 v[186:189], v143 offset:64
	ds_read_b128 v[194:197], v143 offset:1152
	s_waitcnt lgkmcnt(3)
	v_mfma_f32_16x16x32_bf16 v[132:135], v[132:135], v[54:57], 0
	v_add_u32_e32 v144, s25, v138
	v_sub_u32_e32 v142, v144, v142
	v_lshl_add_u32 v181, v142, 2, s19
	s_waitcnt lgkmcnt(2)
	v_mfma_f32_16x16x32_bf16 v[182:185], v[182:185], v[54:57], 0
	v_add_u32_e32 v142, 0x19b60, v181
	s_waitcnt lgkmcnt(1)
	v_mfma_f32_16x16x32_bf16 v[132:135], v[186:189], v[58:61], v[132:135]
	s_waitcnt lgkmcnt(0)
	v_mfma_f32_16x16x32_bf16 v[182:185], v[194:197], v[58:61], v[182:185]
	ds_read_b128 v[186:189], v143 offset:128
	ds_read_b128 v[194:197], v143 offset:1216
	s_waitcnt lgkmcnt(1)
	v_mfma_f32_16x16x32_bf16 v[132:135], v[186:189], v[62:65], v[132:135]
	s_waitcnt lgkmcnt(0)
	v_mfma_f32_16x16x32_bf16 v[182:185], v[194:197], v[62:65], v[182:185]
	ds_read_b128 v[186:189], v143 offset:192
	ds_read_b128 v[194:197], v143 offset:1280
	ds_read2_b32 v[170:171], v142 offset1:1
	v_min_u32_e32 v143, 56, v147
	s_waitcnt lgkmcnt(2)
	v_mfma_f32_16x16x32_bf16 v[186:189], v[186:189], v[66:69], v[132:135]
	s_waitcnt lgkmcnt(1)
	v_mfma_f32_16x16x32_bf16 v[132:135], v[194:197], v[66:69], v[182:185]
	s_waitcnt lgkmcnt(0)
	s_nop 4
	v_add_f32_e32 v142, v186, v170
	v_sub_u32_e32 v184, v144, v143
	v_add_u32_e32 v143, 8, v184
	v_cmp_gt_u32_e32 vcc, 16, v143
	v_add_u32_e32 v144, 10, v184
	s_nop 0
	v_cndmask_b32_e32 v143, v231, v142, vcc
	v_add_u32_e32 v142, 9, v184
	v_cmp_gt_u32_e32 vcc, 16, v142
	v_add_f32_e32 v142, v187, v171
	s_nop 0
	v_cndmask_b32_e32 v142, v231, v142, vcc
	v_cmp_gt_u32_e32 vcc, 16, v144
	v_add_u32_e32 v144, 0x19b68, v181
	ds_read2_b32 v[170:171], v144 offset1:1
	v_max3_f32 v182, v177, v143, v142
	s_waitcnt lgkmcnt(0)
	v_add_f32_e32 v144, v188, v170
	v_cndmask_b32_e32 v147, v231, v144, vcc
	v_add_u32_e32 v144, 11, v184
	v_cmp_gt_u32_e32 vcc, 16, v144
	v_add_f32_e32 v144, v189, v171
	v_add_u32_e32 v170, 12, v184
	v_cndmask_b32_e32 v144, v231, v144, vcc
	v_cmp_gt_u32_e32 vcc, 16, v170
	v_add_u32_e32 v170, 0x19b70, v181
	ds_read2_b32 v[170:171], v170 offset1:1
	v_max3_f32 v182, v182, v147, v144
	s_waitcnt lgkmcnt(0)
	v_add_f32_e32 v132, v132, v170
	v_cndmask_b32_e32 v170, v231, v132, vcc
	v_add_u32_e32 v132, 13, v184
	v_cmp_gt_u32_e32 vcc, 16, v132
	v_add_f32_e32 v132, v133, v171
	v_add_u32_e32 v133, 14, v184
	v_cndmask_b32_e32 v132, v231, v132, vcc
	v_cmp_gt_u32_e32 vcc, 16, v133
	v_add_u32_e32 v133, 0x19b78, v181
	v_max3_f32 v171, v182, v170, v132
	ds_read2_b32 v[182:183], v133 offset1:1
	s_waitcnt lgkmcnt(0)
	v_add_f32_e32 v133, v134, v182
	v_add_u32_e32 v134, 15, v184
	v_cndmask_b32_e32 v133, v231, v133, vcc
	v_cmp_gt_u32_e32 vcc, 16, v134
	v_add_f32_e32 v134, v135, v183
	s_nop 0
	v_cndmask_b32_e32 v134, v231, v134, vcc
	v_max3_f32 v135, v171, v133, v134
	v_mov_b32_e32 v171, v135
	s_nop 1
	v_permlane16_swap_b32_e32 v135, v171
	s_nop 0
	s_waitcnt lgkmcnt(0)
	v_max_f32_e32 v171, v171, v171
	v_max_f32_e32 v135, v135, v171
	v_mov_b32_e32 v171, v135
	s_nop 1
	v_permlane32_swap_b32_e32 v135, v171
	s_nop 0
	s_waitcnt lgkmcnt(0)
	v_max_f32_e32 v171, v171, v171
	v_max_f32_e32 v135, v135, v171
	v_add_f32_e32 v171, 0x41000000, v177
	v_cmp_gt_f32_e32 vcc, v135, v171
	s_cbranch_vccz .LBB0_658
; __device__ __forceinline__ void p_natt(const Frame& F0, const bf16* Q, const bf16* Kb, const bf16* V, const float* rpb, bf16* O, int L) {
;     ...
;                     float alpha = 1.0f;
;                     if (__builtin_amdgcn_ballot_w64(mx > mrun[jt] + 8.0f) != 0ull) { alpha = __expf(mrun[jt] - mx); mrun[jt] = mx;
; #pragma unroll
;                         for (int dt = 0; dt < 8; ++dt) oacc[jt][dt] = oacc[jt][dt] * alpha; }
	v_sub_f32_e32 v130, v177, v135
	v_mul_f32_e32 v130, 0x3fb8aa3b, v130
	v_exp_f32_e32 v130, v130
	v_mov_b32_e32 v177, v135
	v_pk_mul_f32 v[80:81], v[80:81], v[130:131] op_sel_hi:[1,0]
	v_pk_mul_f32 v[78:79], v[78:79], v[130:131] op_sel_hi:[1,0]
	v_pk_mul_f32 v[76:77], v[76:77], v[130:131] op_sel_hi:[1,0]
	v_pk_mul_f32 v[74:75], v[74:75], v[130:131] op_sel_hi:[1,0]
	v_pk_mul_f32 v[72:73], v[72:73], v[130:131] op_sel_hi:[1,0]
	v_pk_mul_f32 v[70:71], v[70:71], v[130:131] op_sel_hi:[1,0]
	v_pk_mul_f32 v[44:45], v[44:45], v[130:131] op_sel_hi:[1,0]
	v_pk_mul_f32 v[42:43], v[42:43], v[130:131] op_sel_hi:[1,0]
	v_pk_mul_f32 v[24:25], v[24:25], v[130:131] op_sel_hi:[1,0]
	v_pk_mul_f32 v[22:23], v[22:23], v[130:131] op_sel_hi:[1,0]
	v_pk_mul_f32 v[20:21], v[20:21], v[130:131] op_sel_hi:[1,0]
	v_pk_mul_f32 v[18:19], v[18:19], v[130:131] op_sel_hi:[1,0]
	v_pk_mul_f32 v[8:9], v[8:9], v[130:131] op_sel_hi:[1,0]
	v_pk_mul_f32 v[6:7], v[6:7], v[130:131] op_sel_hi:[1,0]
	v_pk_mul_f32 v[4:5], v[4:5], v[130:131] op_sel_hi:[1,0]
	v_pk_mul_f32 v[2:3], v[2:3], v[130:131] op_sel_hi:[1,0]
	s_branch .LBB0_659

; #define LAS __attribute__((address_space(3)))
; __device__ __forceinline__ unsigned pk2(float lo, float hi) { f32x2 v = {lo, hi}; bf16x2_t b = __builtin_convertvector(v, bf16x2_t); return __builtin_bit_cast(unsigned, b); }
; __device__ __forceinline__ float shfl_lane(float v, int srclane) { return __int_as_float(__builtin_amdgcn_ds_bpermute(srclane << 2, __float_as_int(v))); }
; __device__ __forceinline__ s16x4 tr_read(const LAS unsigned char* p) { return __builtin_bit_cast(s16x4, __builtin_amdgcn_ds_read_tr16_b64_v4i16((LAS v4i16_t*)p)); }
; __device__ __forceinline__ bf16x8 cat8(s16x4 lo, s16x4 hi) { return __builtin_shufflevector(lo, hi, 0, 1, 2, 3, 4, 5, 6, 7); }
; __device__ __forceinline__ void p_natt(const Frame& F0, const bf16* Q, const bf16* Kb, const bf16* V, const float* rpb, bf16* O, int L) {
;     ...
;                     mx = mrun[jt];
;                     float ps = 0.f;
; #pragma unroll
;                     for (int e = 0; e < 8; ++e) { sv[e] = __expf(sv[e] - mx); ps += sv[e]; }
;                     ps += shfl_lane(ps, Lq ^ 16); ps += shfl_lane(ps, Lq ^ 32);
;                     lrun[jt] = lrun[jt] * alpha + ps;
;                     u32x4 pw; pw.x = pk2(sv[0], sv[1]); pw.y = pk2(sv[2], sv[3]); pw.z = pk2(sv[4], sv[5]); pw.w = pk2(sv[6], sv[7]);
;                     const bf16x8 pf = __builtin_bit_cast(bf16x8, pw);
;                     const LAS unsigned char* va = vb + (kstart + 8 * g + q4) * PB + 8 * p4;
; #pragma unroll
;                     for (int dt = 0; dt < 8; ++dt) { const bf16x8 vf = cat8(tr_read(va + 32 * dt), tr_read(va + 4 * PB + 32 * dt));
;                         oacc[jt][dt] = __builtin_amdgcn_mfma_f32_16x16x32_bf16(vf, pf, oacc[jt][dt], 0, 0, 0); }
.LBB0_659:
	v_add_f32_e32 v145, v145, v146
	v_fmac_f32_e32 v145, v179, v136
	v_sub_f32_e32 v136, v143, v135
	v_mul_f32_e32 v136, 0x3fb8aa3b, v136
	v_sub_f32_e32 v142, v142, v135
	v_exp_f32_e32 v136, v136
	v_mul_f32_e32 v142, 0x3fb8aa3b, v142
	v_sub_f32_e32 v146, v147, v135
	v_exp_f32_e32 v142, v142
	v_mul_f32_e32 v146, 0x3fb8aa3b, v146
	v_sub_f32_e32 v144, v144, v135
	v_exp_f32_e32 v146, v146
	v_mul_f32_e32 v144, 0x3fb8aa3b, v144
	v_sub_f32_e32 v147, v170, v135
	v_exp_f32_e32 v144, v144
	v_mul_f32_e32 v147, 0x3fb8aa3b, v147
	v_sub_f32_e32 v132, v132, v135
	v_add_f32_e32 v143, 0, v136
	v_exp_f32_e32 v147, v147
	v_mul_f32_e32 v132, 0x3fb8aa3b, v132
	v_add_f32_e32 v143, v142, v143
	v_exp_f32_e32 v170, v132
	v_add_f32_e32 v143, v146, v143
	v_add_f32_e32 v143, v144, v143
	v_sub_f32_e32 v133, v133, v135
	v_add_f32_e32 v143, v147, v143
	v_mul_f32_e32 v133, 0x3fb8aa3b, v133
	v_add_f32_e32 v132, v170, v143
	v_exp_f32_e32 v143, v133
	v_sub_f32_e32 v133, v134, v135
	v_mul_f32_e32 v133, 0x3fb8aa3b, v133
	v_exp_f32_e32 v135, v133
	v_add_f32_e32 v132, v143, v132
	v_cvt_pk_bf16_f32 v134, v147, v170
	v_mov_b32_e32 v179, v145
	v_add_f32_e32 v132, v135, v132
	v_mov_b32_e32 v133, v132
	s_nop 1
	v_permlane16_swap_b32_e32 v132, v133
	s_nop 0
	v_cvt_pk_bf16_f32 v135, v143, v135
	s_waitcnt lgkmcnt(0)
	v_add_f32_e32 v132, v132, v133
	v_mov_b32_e32 v133, v132
	s_nop 1
	v_permlane32_swap_b32_e32 v132, v133
	s_nop 0
	s_waitcnt lgkmcnt(0)
	v_add_f32_e32 v171, v132, v133
	v_fmac_f32_e32 v171, v178, v130
	v_add3_u32 v130, s25, v137, v138
	v_mul_lo_u32 v130, v130, s38
	v_add3_u32 v130, v130, v141, s18
	v_cvt_pk_bf16_f32 v132, v136, v142
	ds_read_b64_tr_b16 v[138:139], v130 offset:18496
	ds_read_b64_tr_b16 v[136:137], v130 offset:17408
	ds_read_b64_tr_b16 v[140:141], v130 offset:17440
	v_cvt_pk_bf16_f32 v133, v146, v144
	ds_read_b64_tr_b16 v[142:143], v130 offset:18528
	v_mov_b32_e32 v178, v171
	s_waitcnt lgkmcnt(2)
	v_mfma_f32_16x16x32_bf16 v[78:81], v[136:139], v[132:135], v[78:81]
	ds_read_b64_tr_b16 v[136:137], v130 offset:17472
	ds_read_b64_tr_b16 v[138:139], v130 offset:18560
	s_waitcnt lgkmcnt(0)
	v_mfma_f32_16x16x32_bf16 v[70:73], v[136:139], v[132:135], v[70:73]
	ds_read_b64_tr_b16 v[136:137], v130 offset:17504
	ds_read_b64_tr_b16 v[138:139], v130 offset:18592
	s_waitcnt lgkmcnt(0)
	v_mfma_f32_16x16x32_bf16 v[42:45], v[136:139], v[132:135], v[42:45]
	ds_read_b64_tr_b16 v[136:137], v130 offset:17536
	ds_read_b64_tr_b16 v[138:139], v130 offset:18624
	s_waitcnt lgkmcnt(0)
	v_mfma_f32_16x16x32_bf16 v[22:25], v[136:139], v[132:135], v[22:25]
	ds_read_b64_tr_b16 v[136:137], v130 offset:17568
	ds_read_b64_tr_b16 v[138:139], v130 offset:18656
	s_waitcnt lgkmcnt(0)
	v_mfma_f32_16x16x32_bf16 v[18:21], v[136:139], v[132:135], v[18:21]
	ds_read_b64_tr_b16 v[136:137], v130 offset:17600
	ds_read_b64_tr_b16 v[138:139], v130 offset:18688
	s_waitcnt lgkmcnt(0)
	v_mfma_f32_16x16x32_bf16 v[6:9], v[136:139], v[132:135], v[6:9]
	ds_read_b64_tr_b16 v[136:137], v130 offset:17632
	ds_read_b64_tr_b16 v[138:139], v130 offset:18720
	v_mfma_f32_16x16x32_bf16 v[74:77], v[140:143], v[132:135], v[74:77]
	s_waitcnt lgkmcnt(0)
	v_mfma_f32_16x16x32_bf16 v[2:5], v[136:139], v[132:135], v[2:5]
	s_add_i32 s0, s31, 2
	s_cmp_gt_i32 s0, s17
	s_cbranch_scc1 .LBB0_665
